# attention loop back-edge rotated: per-tile iteration classification moved ahead of the barrier so LDS reads issue right after it
# speedup vs baseline: 1.0090x; 1.0090x over previous
; #define LAS __attribute__((address_space(3)))
; __device__ __forceinline__ float fast_exp2(float x) { return __builtin_amdgcn_exp2f(x); }
; #define LGK(n, f) asm volatile("s_waitcnt lgkmcnt(%1)" : "+v"(f) : "n"(n))
; #define ATT_KRD(i) DSR(fr_[(i) & 3], kad[((i) >> 1) & 3], ((i) & 1) * (32 * 384) + ((i) >> 3) * 128)
; __device__ __forceinline__ void attn_phase(int wv, const bf16_t* Q, const bf16_t* Kf, const bf16_t* Vt, const bf16_t* proj, bf16_t* mixed, LAS unsigned char* lds) { LIDS
;     ...
;             for (int t = 0; t < nt; ++t) {
;                 const int b = t & 1;
;                 asm volatile("s_waitcnt vmcnt(0)" ::: "memory"); __builtin_amdgcn_s_barrier(); asm volatile("" ::: "memory");
;                 if (t + 1 < nt) ATT_ISSUE(t + 1, b ^ 1);
;                 if (64 * t <= qw0 + 31) {
;                     LAS unsigned char* kb_ = lds + b * ATT_STAGE; LAS unsigned char* vb_ = kb_ + ATT_KB;
;                     f32x16 s[2];
; #pragma unroll
;                     for (int kb = 0; kb < 2; ++kb)
; #pragma unroll
;                         for (int j = 0; j < 16; ++j) s[kb][j] = zf;
;                     unsigned kad[4];
; #pragma unroll
;                     for (int kl = 0; kl < 4; ++kl) kad[kl] = (unsigned)(size_t)kb_ + (unsigned)koffl[kl];
;                     bf16x8 fr_[4];
;     ...
;                     ATT_KRD(0); ATT_KRD(1); ATT_KRD(2); ATT_KRD(3);
; #pragma unroll
;                     for (int i = 0; i < 24; ++i) {
;                         LGK(i < 21 ? 3 : 23 - i, fr_[i & 3]);
;                         s[i & 1] = __builtin_amdgcn_mfma_f32_32x32x16_bf16(fr_[i & 3], qf[i >> 1], s[i & 1], 0, 0, 0);
;                         if (i + 4 < 24) ATT_KRD(i + 4);
;                     }
;     ...
;                     float ps = 0.f;
; #pragma unroll
;                     for (int kb = 0; kb < 2; ++kb)
; #pragma unroll
;                         for (int j = 0; j < 16; ++j) { s[kb][j] = fast_exp2(s[kb][j] - mrun); ps += s[kb][j]; }
;                     lsum += ps;
.Lp2_loop0:
	s_add_i32 s22, s19, 2
	s_add_i32 s24, s19, 1
	s_cmp_gt_i32 s19, s21
	s_cbranch_scc1 .Lp2_idle0
	s_cmp_eq_u32 s19, s21
	s_cbranch_scc1 .Lp2_drain0
.Lp2_top0:
	s_waitcnt vmcnt(0)
	s_barrier
	ds_read_b128 v[160:163], v207 offset:0xa010
	ds_read_b128 v[164:167], v207 offset:0xd010
	ds_read_b128 v[168:171], v208 offset:0xa010
	ds_read_b128 v[172:175], v208 offset:0xd010
	s_waitcnt lgkmcnt(3)
	v_mfma_f32_32x32x16_bf16 v[228:243], v[160:163], v[112:115], v[0:15]
	ds_read_b128 v[160:163], v209 offset:0xa010
	v_exp_f32_e32 v96, v96
	v_exp_f32_e32 v97, v97
	s_nop 0
	v_add_f32_e32 v246, v96, v97
	s_waitcnt lgkmcnt(3)
	v_mfma_f32_32x32x16_bf16 v[178:193], v[164:167], v[112:115], v[0:15]
	ds_read_b128 v[164:167], v209 offset:0xd010
	v_cvt_pk_bf16_f32 v96, v96, v97
	v_exp_f32_e32 v98, v98
	v_exp_f32_e32 v99, v99
	s_cmp_ge_i32 s22, s17
	s_cbranch_scc1 .Lp2_nd3
	s_mov_b32 m0, s58
	s_nop 0
	global_load_lds_dwordx4 v176, s[62:63]

; __device__ __forceinline__ unsigned cvt_pk_bf16(float lo, float hi) { unsigned r; asm volatile("v_cvt_pk_bf16_f32 %0, %1, %2" : "=v"(r) : "v"(lo), "v"(hi)); return r; }
; __device__ __forceinline__ float fast_exp2(float x) { return __builtin_amdgcn_exp2f(x); }
; #define LGK(n, f) asm volatile("s_waitcnt lgkmcnt(%1)" : "+v"(f) : "n"(n))
; #define ATT_VRD(j) DSR(fr_[(j) & 3], vad[(j) >> 2], ((j) & 3) * 4096)
; __device__ __forceinline__ void attn_phase(int wv, const bf16_t* Q, const bf16_t* Kf, const bf16_t* Vt, const bf16_t* proj, bf16_t* mixed, LAS unsigned char* lds) { LIDS
;     ...
;                     float mx = -1e30f;
; #pragma unroll
;                     for (int kb = 0; kb < 2; ++kb)
; #pragma unroll
;                         for (int j = 0; j < 16; ++j) mx = fmaxf(mx, s[kb][j]);
;                     mx = fmaxf(mx, __shfl_xor(mx, 32));
;                     if (__builtin_amdgcn_ballot_w64(mx > mrun + 8.0f) != 0ull) {
;                         const float mnew = fmaxf(mrun, mx), alpha = fast_exp2(mrun - mnew); mrun = mnew;
;                         lsum *= alpha;
; #pragma unroll
;                         for (int bb = 0; bb < 4; ++bb)
; #pragma unroll
;                             for (int j = 0; j < 16; ++j) o[bb][j] *= alpha;
;                     }
;                     float ps = 0.f;
; #pragma unroll
;                     for (int kb = 0; kb < 2; ++kb)
; #pragma unroll
;                         for (int j = 0; j < 16; ++j) { s[kb][j] = fast_exp2(s[kb][j] - mrun); ps += s[kb][j]; }
;                     lsum += ps;
; #pragma unroll
;                     for (int c = 0; c < 4; ++c) {
;                         const int kb = c >> 1, sx = c & 1;
;                         u32x4 pw;
; #pragma unroll
;                         for (int j = 0; j < 4; ++j) pw[j] = cvt_pk_bf16(s[kb][8 * sx + 2 * j], s[kb][8 * sx + 2 * j + 1]);
;                         const bf16x8 pf = __builtin_bit_cast(bf16x8, pw);
; #pragma unroll
;                         for (int bb = 0; bb < 4; ++bb) {
;                             const int j = c * 4 + bb;
;                             LGK(j < 13 ? 3 : 15 - j, fr_[j & 3]);
;                             o[bb] = __builtin_amdgcn_mfma_f32_32x32x16_bf16(fr_[j & 3], pf, o[bb], 0, 0, 0);
;                             if (j + 4 < 16) ATT_VRD(j + 4);
;                         }
.Lp2_nomask2:
	s_waitcnt lgkmcnt(3)
	v_mfma_f32_32x32x16_bf16 v[48:63], v[160:163], v[100:103], v[48:63]
	ds_read_b128 v[160:163], v220 offset:0x6010
	v_max3_f32 v226, v228, v229, v230
	v_max3_f32 v226, v226, v231, v232
	v_max3_f32 v226, v226, v233, v234
	v_max3_f32 v226, v226, v235, v236
	v_max3_f32 v226, v226, v237, v238
	s_waitcnt lgkmcnt(3)
	v_mfma_f32_32x32x16_bf16 v[32:47], v[164:167], v[100:103], v[32:47]
	ds_read_b128 v[164:167], v220 offset:0x7010
	v_max3_f32 v226, v226, v239, v240
	v_max3_f32 v226, v226, v241, v242
	v_max_f32_e32 v226, v226, v243
	v_max3_f32 v227, v178, v179, v180
	v_max3_f32 v227, v227, v181, v182
	s_waitcnt lgkmcnt(3)
	v_mfma_f32_32x32x16_bf16 v[16:31], v[168:171], v[100:103], v[16:31]
	ds_read_b128 v[168:171], v220 offset:0x8010
	v_max3_f32 v227, v227, v183, v184
	v_max3_f32 v227, v227, v185, v186
	v_max3_f32 v227, v227, v187, v188
	v_max3_f32 v227, v227, v189, v190
	v_max3_f32 v227, v227, v191, v192
	s_waitcnt lgkmcnt(3)
	v_mfma_f32_32x32x16_bf16 v[64:79], v[172:175], v[100:103], v[64:79]
	ds_read_b128 v[172:175], v220 offset:0x9010
	v_max_f32_e32 v227, v227, v193
	v_max_f32_e32 v226, v226, v227
	v_mov_b32_e32 v227, v226
	s_nop 1
	v_permlane32_swap_b32_e32 v226, v227
	v_max_f32_e32 v226, v226, v227
	s_waitcnt lgkmcnt(3)
	v_mfma_f32_32x32x16_bf16 v[48:63], v[160:163], v[80:83], v[48:63]
	ds_read_b128 v[160:163], v221 offset:0x6010
	s_waitcnt lgkmcnt(3)
	v_mfma_f32_32x32x16_bf16 v[32:47], v[164:167], v[80:83], v[32:47]
	ds_read_b128 v[164:167], v221 offset:0x7010
	s_waitcnt lgkmcnt(3)
	v_mfma_f32_32x32x16_bf16 v[16:31], v[168:171], v[80:83], v[16:31]
	ds_read_b128 v[168:171], v221 offset:0x8010
	s_waitcnt lgkmcnt(3)
	v_mfma_f32_32x32x16_bf16 v[64:79], v[172:175], v[80:83], v[64:79]
	ds_read_b128 v[172:175], v221 offset:0x9010
	s_waitcnt lgkmcnt(3)
	v_mfma_f32_32x32x16_bf16 v[48:63], v[160:163], v[84:87], v[48:63]
	s_waitcnt lgkmcnt(2)
	v_mfma_f32_32x32x16_bf16 v[32:47], v[164:167], v[84:87], v[32:47]
	s_waitcnt lgkmcnt(1)
	v_mfma_f32_32x32x16_bf16 v[16:31], v[168:171], v[84:87], v[16:31]
	s_waitcnt lgkmcnt(0)
	v_mfma_f32_32x32x16_bf16 v[64:79], v[172:175], v[84:87], v[64:79]
	v_cmp_gt_f32_e32 vcc, v226, v247
	s_cbranch_vccnz .Lp2_rare0
.Lp2_tail0:
	s_add_i32 s19, s19, 1
	s_add_u32 s62, s62, 0x30000
	s_addc_u32 s63, s63, 0
	s_add_u32 s72, s72, 0x80
	s_addc_u32 s73, s73, 0
	s_cmp_eq_u32 s19, s17
	s_cbranch_scc1 .Lp2_exit
	s_add_i32 s22, s19, 2
	s_add_i32 s24, s19, 1
	s_cmp_gt_i32 s19, s21
	s_cbranch_scc1 .Lp2_idle1
	s_cmp_eq_u32 s19, s21
	s_cbranch_scc1 .Lp2_drain1
.Lp2_top1:
	s_waitcnt vmcnt(0)
	s_barrier
	ds_read_b128 v[160:163], v207 offset:0x10
	ds_read_b128 v[164:167], v207 offset:0x3010
	ds_read_b128 v[168:171], v208 offset:0x10
	ds_read_b128 v[172:175], v208 offset:0x3010
	s_waitcnt lgkmcnt(3)
	v_mfma_f32_32x32x16_bf16 v[96:111], v[160:163], v[112:115], v[0:15]
	ds_read_b128 v[160:163], v209 offset:0x10
	v_exp_f32_e32 v228, v228
	v_exp_f32_e32 v229, v229
	s_nop 0
	v_add_f32_e32 v246, v228, v229
	s_waitcnt lgkmcnt(3)
	v_mfma_f32_32x32x16_bf16 v[80:95], v[164:167], v[112:115], v[0:15]
	ds_read_b128 v[164:167], v209 offset:0x3010
	v_cvt_pk_bf16_f32 v228, v228, v229
	v_exp_f32_e32 v230, v230
	v_exp_f32_e32 v231, v231
	s_cmp_ge_i32 s22, s17
	s_cbranch_scc1 .Lp2_nd9
	s_add_i32 m0, s58, 0xa000
	s_nop 0
	global_load_lds_dwordx4 v176, s[62:63]

; __device__ __forceinline__ float fast_exp2(float x) { return __builtin_amdgcn_exp2f(x); }
; __device__ __forceinline__ void attn_phase(int wv, const bf16_t* Q, const bf16_t* Kf, const bf16_t* Vt, const bf16_t* proj, bf16_t* mixed, LAS unsigned char* lds) { LIDS
;     ...
;             for (int t = 0; t < nt; ++t) {
;                 const int b = t & 1;
;                 asm volatile("s_waitcnt vmcnt(0)" ::: "memory"); __builtin_amdgcn_s_barrier(); asm volatile("" ::: "memory");
;                 if (t + 1 < nt) ATT_ISSUE(t + 1, b ^ 1);
;                 if (64 * t <= qw0 + 31) {
;     ...
;                     float mx = -1e30f;
; #pragma unroll
;                     for (int kb = 0; kb < 2; ++kb)
; #pragma unroll
;                         for (int j = 0; j < 16; ++j) mx = fmaxf(mx, s[kb][j]);
;                     mx = fmaxf(mx, __shfl_xor(mx, 32));
;                     if (__builtin_amdgcn_ballot_w64(mx > mrun + 8.0f) != 0ull) {
;                         const float mnew = fmaxf(mrun, mx), alpha = fast_exp2(mrun - mnew); mrun = mnew;
;                         lsum *= alpha;
; #pragma unroll
;                         for (int bb = 0; bb < 4; ++bb)
; #pragma unroll
;                             for (int j = 0; j < 16; ++j) o[bb][j] *= alpha;
;                     }
;                     float ps = 0.f;
; #pragma unroll
;                     for (int kb = 0; kb < 2; ++kb)
; #pragma unroll
;                         for (int j = 0; j < 16; ++j) { s[kb][j] = fast_exp2(s[kb][j] - mrun); ps += s[kb][j]; }
;                     lsum += ps;
; #pragma unroll
;                     for (int c = 0; c < 4; ++c) {
;                         const int kb = c >> 1, sx = c & 1;
;                         u32x4 pw;
; #pragma unroll
;                         for (int j = 0; j < 4; ++j) pw[j] = cvt_pk_bf16(s[kb][8 * sx + 2 * j], s[kb][8 * sx + 2 * j + 1]);
;                         const bf16x8 pf = __builtin_bit_cast(bf16x8, pw);
; #pragma unroll
;                         for (int bb = 0; bb < 4; ++bb) {
;                             const int j = c * 4 + bb;
;                             LGK(j < 13 ? 3 : 15 - j, fr_[j & 3]);
;                             o[bb] = __builtin_amdgcn_mfma_f32_32x32x16_bf16(fr_[j & 3], pf, o[bb], 0, 0, 0);
;                             if (j + 4 < 16) ATT_VRD(j + 4);
;                         }
;                     }
.Lp2_nomask8:
	s_waitcnt lgkmcnt(3)
	v_mfma_f32_32x32x16_bf16 v[48:63], v[160:163], v[232:235], v[48:63]
	ds_read_b128 v[160:163], v212 offset:0x8010
	v_max3_f32 v226, v96, v97, v98
	v_max3_f32 v226, v226, v99, v100
	v_max3_f32 v226, v226, v101, v102
	v_max3_f32 v226, v226, v103, v104
	v_max3_f32 v226, v226, v105, v106
	s_waitcnt lgkmcnt(3)
	v_mfma_f32_32x32x16_bf16 v[32:47], v[164:167], v[232:235], v[32:47]
	ds_read_b128 v[164:167], v212 offset:0x9010
	v_max3_f32 v226, v226, v107, v108
	v_max3_f32 v226, v226, v109, v110
	v_max_f32_e32 v226, v226, v111
	v_max3_f32 v227, v80, v81, v82
	v_max3_f32 v227, v227, v83, v84
	s_waitcnt lgkmcnt(3)
	v_mfma_f32_32x32x16_bf16 v[16:31], v[168:171], v[232:235], v[16:31]
	ds_read_b128 v[168:171], v212 offset:0xa010
	v_max3_f32 v227, v227, v85, v86
	v_max3_f32 v227, v227, v87, v88
	v_max3_f32 v227, v227, v89, v90
	v_max3_f32 v227, v227, v91, v92
	v_max3_f32 v227, v227, v93, v94
	s_waitcnt lgkmcnt(3)
	v_mfma_f32_32x32x16_bf16 v[64:79], v[172:175], v[232:235], v[64:79]
	ds_read_b128 v[172:175], v212 offset:0xb010
	v_max_f32_e32 v227, v227, v95
	v_max_f32_e32 v226, v226, v227
	v_mov_b32_e32 v227, v226
	s_nop 1
	v_permlane32_swap_b32_e32 v226, v227
	v_max_f32_e32 v226, v226, v227
	s_waitcnt lgkmcnt(3)
	v_mfma_f32_32x32x16_bf16 v[48:63], v[160:163], v[178:181], v[48:63]
	ds_read_b128 v[160:163], v213 offset:0x8010
	s_waitcnt lgkmcnt(3)
	v_mfma_f32_32x32x16_bf16 v[32:47], v[164:167], v[178:181], v[32:47]
	ds_read_b128 v[164:167], v213 offset:0x9010
	s_waitcnt lgkmcnt(3)
	v_mfma_f32_32x32x16_bf16 v[16:31], v[168:171], v[178:181], v[16:31]
	ds_read_b128 v[168:171], v213 offset:0xa010
	s_waitcnt lgkmcnt(3)
	v_mfma_f32_32x32x16_bf16 v[64:79], v[172:175], v[178:181], v[64:79]
	ds_read_b128 v[172:175], v213 offset:0xb010
	s_waitcnt lgkmcnt(3)
	v_mfma_f32_32x32x16_bf16 v[48:63], v[160:163], v[182:185], v[48:63]
	s_waitcnt lgkmcnt(2)
	v_mfma_f32_32x32x16_bf16 v[32:47], v[164:167], v[182:185], v[32:47]
	s_waitcnt lgkmcnt(1)
	v_mfma_f32_32x32x16_bf16 v[16:31], v[168:171], v[182:185], v[16:31]
	s_waitcnt lgkmcnt(0)
	v_mfma_f32_32x32x16_bf16 v[64:79], v[172:175], v[182:185], v[64:79]
	v_cmp_gt_f32_e32 vcc, v226, v247
	s_cbranch_vccnz .Lp2_rare1
.Lp2_tail1:
	s_add_i32 s19, s19, 1
	s_add_u32 s62, s62, 0x30000
	s_addc_u32 s63, s63, 0
	s_add_u32 s72, s72, 0x80
	s_addc_u32 s73, s73, 0
	s_cmp_eq_u32 s19, s17
	s_cbranch_scc1 .Lp2_exit
	s_add_i32 s22, s19, 2
	s_add_i32 s24, s19, 1
	s_cmp_gt_i32 s19, s21
	s_cbranch_scc1 .Lp2_idle0
	s_cmp_eq_u32 s19, s21
	s_cbranch_scc1 .Lp2_drain0
	s_branch .Lp2_top0

; __device__ __forceinline__ void attn_phase(int wv, const bf16_t* Q, const bf16_t* Kf, const bf16_t* Vt, const bf16_t* proj, bf16_t* mixed, LAS unsigned char* lds) { LIDS
;     ...
;                 asm volatile("s_waitcnt vmcnt(0)" ::: "memory"); __builtin_amdgcn_s_barrier(); asm volatile("" ::: "memory");
;                 if (t + 1 < nt) ATT_ISSUE(t + 1, b ^ 1);
;                 if (64 * t <= qw0 + 31) {
.Lp2_idle0:
	s_waitcnt vmcnt(0)
	s_barrier
	s_cmp_ge_i32 s22, s17
	s_cbranch_scc1 .Lp2_nd14
	s_mov_b32 m0, s58
	s_nop 0
	global_load_lds_dwordx4 v176, s[62:63]

; __device__ __forceinline__ void attn_phase(int wv, const bf16_t* Q, const bf16_t* Kf, const bf16_t* Vt, const bf16_t* proj, bf16_t* mixed, LAS unsigned char* lds) { LIDS
;     ...
;                 asm volatile("s_waitcnt vmcnt(0)" ::: "memory"); __builtin_amdgcn_s_barrier(); asm volatile("" ::: "memory");
;                 if (t + 1 < nt) ATT_ISSUE(t + 1, b ^ 1);
;                 if (64 * t <= qw0 + 31) {
.Lp2_idle1:
	s_waitcnt vmcnt(0)
	s_barrier
	s_cmp_ge_i32 s22, s17
	s_cbranch_scc1 .Lp2_nd19
	s_add_i32 m0, s58, 0xa000
	s_nop 0
	global_load_lds_dwordx4 v176, s[62:63]

; #define ATT_VRD(j) DSR(fr_[(j) & 3], vad[(j) >> 2], ((j) & 3) * 4096)
; __device__ __forceinline__ void attn_phase(int wv, const bf16_t* Q, const bf16_t* Kf, const bf16_t* Vt, const bf16_t* proj, bf16_t* mixed, LAS unsigned char* lds) { LIDS
;     ...
;                 asm volatile("s_waitcnt vmcnt(0)" ::: "memory"); __builtin_amdgcn_s_barrier(); asm volatile("" ::: "memory");
;                 if (t + 1 < nt) ATT_ISSUE(t + 1, b ^ 1);
;     ...
;                     unsigned vad[4];
; #pragma unroll
;                     for (int c = 0; c < 4; ++c) vad[c] = (unsigned)(size_t)vb_ + (unsigned)voffl[c];
;     ...
;                     ATT_VRD(0); ATT_VRD(1); ATT_VRD(2); ATT_VRD(3);
.Lp2_drain0:
	s_waitcnt vmcnt(0)
	s_barrier
	ds_read_b128 v[160:163], v218 offset:0x6010
	ds_read_b128 v[164:167], v218 offset:0x7010
	ds_read_b128 v[168:171], v218 offset:0x8010
	ds_read_b128 v[172:175], v218 offset:0x9010
	s_cmp_ge_i32 s22, s17
	s_cbranch_scc1 .Lp2_nd24
	s_mov_b32 m0, s58
	s_nop 0
	global_load_lds_dwordx4 v176, s[62:63]

; #define ATT_VRD(j) DSR(fr_[(j) & 3], vad[(j) >> 2], ((j) & 3) * 4096)
; __device__ __forceinline__ void attn_phase(int wv, const bf16_t* Q, const bf16_t* Kf, const bf16_t* Vt, const bf16_t* proj, bf16_t* mixed, LAS unsigned char* lds) { LIDS
;     ...
;                 asm volatile("s_waitcnt vmcnt(0)" ::: "memory"); __builtin_amdgcn_s_barrier(); asm volatile("" ::: "memory");
;                 if (t + 1 < nt) ATT_ISSUE(t + 1, b ^ 1);
;     ...
;                     unsigned vad[4];
; #pragma unroll
;                     for (int c = 0; c < 4; ++c) vad[c] = (unsigned)(size_t)vb_ + (unsigned)voffl[c];
;     ...
;                     ATT_VRD(0); ATT_VRD(1); ATT_VRD(2); ATT_VRD(3);
.Lp2_drain1:
	s_waitcnt vmcnt(0)
	s_barrier
	ds_read_b128 v[160:163], v210 offset:0x8010
	ds_read_b128 v[164:167], v210 offset:0x9010
	ds_read_b128 v[168:171], v210 offset:0xa010
	ds_read_b128 v[172:175], v210 offset:0xb010
	s_cmp_ge_i32 s22, s17
	s_cbranch_scc1 .Lp2_nd29
	s_add_i32 m0, s58, 0xa000
	s_nop 0
	global_load_lds_dwordx4 v176, s[62:63]
